# v_full12 + 64-bit clears also for the two shorter zero-initialisation runs (S2 scan prologue, early setup)
# baseline (speedup 1.0000x reference)
.LBB0_54:
	v_bfe_u32 v2, v23, 8, 1
	v_ashrrev_i32_e32 v24, 6, v22
	v_cmp_eq_u32_e32 vcc, s22, v2
	v_mov_b32_e32 v2, 0
	v_mov_b32_e32 v25, 0
	v_mov_b64_e32 v[26:27], 0
	v_mov_b64_e32 v[28:29], 0
	v_mov_b64_e32 v[30:31], 0
	s_and_saveexec_b64 s[84:85], vcc
	s_cbranch_execz .LBB0_53
	v_bfe_u32 v2, v22, 6, 6
	v_bfe_u32 v25, v23, 4, 4
	v_mul_u32_u24_e32 v27, 17, v2
	v_sub_u32_e32 v25, v27, v25
	v_lshl_add_u32 v25, v25, 2, 0
	v_and_b32_e32 v26, 8, v23
	v_add_u32_e32 v25, 60, v25
	ds_read2st64_b32 v[42:43], v25 offset1:17
	v_lshlrev_b32_e32 v25, 2, v26
	v_lshl_or_b32 v2, v2, 6, v25
	v_add_u32_e32 v2, 0, v2
	ds_read_b128 v[26:29], v2 offset:12800
	ds_read_b128 v[30:33], v2 offset:8704
	ds_read_b128 v[34:37], v2 offset:8720
	s_waitcnt lgkmcnt(3)
	v_mov_b32_e32 v44, v43
	ds_read_b128 v[38:41], v2 offset:12816
	s_waitcnt lgkmcnt(3)
	v_pk_mul_f32 v[46:47], v[44:45], v[26:27] op_sel_hi:[0,1]
	v_pk_mul_f32 v[26:27], v[42:43], v[26:27] op_sel_hi:[0,1]
	s_waitcnt lgkmcnt(2)
	v_pk_fma_f32 v[46:47], v[42:43], v[30:31], v[46:47] op_sel_hi:[0,1,1] neg_lo:[0,0,1] neg_hi:[0,0,1]
	v_pk_fma_f32 v[26:27], v[44:45], v[30:31], v[26:27] op_sel_hi:[0,1,1]
	v_cmp_gt_i32_e32 vcc, 64, v24
	s_waitcnt lgkmcnt(0)
	v_pk_mul_f32 v[30:31], v[42:43], v[38:39] op_sel_hi:[0,1]
	v_pk_fma_f32 v[30:31], v[44:45], v[34:35], v[30:31] op_sel_hi:[0,1,1]
	v_cndmask_b32_e32 v2, v26, v46, vcc
	v_cndmask_b32_e32 v25, v27, v47, vcc
	v_pk_mul_f32 v[26:27], v[44:45], v[28:29] op_sel_hi:[0,1]
	v_pk_mul_f32 v[28:29], v[42:43], v[28:29] op_sel_hi:[0,1]
	v_pk_fma_f32 v[26:27], v[42:43], v[32:33], v[26:27] op_sel_hi:[0,1,1] neg_lo:[0,0,1] neg_hi:[0,0,1]
	v_pk_fma_f32 v[28:29], v[44:45], v[32:33], v[28:29] op_sel_hi:[0,1,1]
	v_cndmask_b32_e32 v26, v28, v26, vcc
	v_cndmask_b32_e32 v27, v29, v27, vcc
	v_pk_mul_f32 v[28:29], v[44:45], v[38:39] op_sel_hi:[0,1]
	v_pk_fma_f32 v[28:29], v[42:43], v[34:35], v[28:29] op_sel_hi:[0,1,1] neg_lo:[0,0,1] neg_hi:[0,0,1]
	v_cndmask_b32_e32 v28, v30, v28, vcc
	v_cndmask_b32_e32 v29, v31, v29, vcc
	v_mov_b32_e32 v30, v36
	v_mov_b32_e32 v31, v40
	v_pk_mul_f32 v[32:33], v[42:43], v[30:31]
	v_mov_b32_e32 v40, v37
	v_sub_f32_e32 v34, v32, v33
	v_mov_b32_e32 v32, v43
	v_mov_b32_e32 v33, v42
	v_pk_mul_f32 v[30:31], v[32:33], v[30:31]
	v_pk_mul_f32 v[32:33], v[32:33], v[40:41]
	v_add_f32_e32 v30, v30, v31
	v_cndmask_b32_e32 v30, v30, v34, vcc
	v_pk_mul_f32 v[34:35], v[42:43], v[40:41]
	v_add_f32_e32 v32, v32, v33
	v_sub_f32_e32 v31, v34, v35
	v_cndmask_b32_e32 v31, v32, v31, vcc
	s_branch .LBB0_53

.LBB0_347:
	s_or_b64 exec, exec, s[0:1]
	s_waitcnt lgkmcnt(0)
	v_mov_b32_e32 v0, v180
	v_mov_b32_e32 v1, v180
	s_barrier
	s_mov_b32 s14, s95
	v_and_b32_e32 v0, 63, v0
	s_cmpk_gt_i32 s14, 0x7f
	v_ashrrev_i32_e32 v1, 6, v1
	s_cbranch_scc1 .LBB0_380
	v_lshl_add_u32 v4, v1, 7, v1
	v_min_i32_e32 v3, 0x380, v4
	v_add_u32_e32 v5, 0x79, v3
	v_cmp_le_i32_e64 s[2:3], v4, v5
	v_ashrrev_i32_e32 v5, 31, v4
	v_lshlrev_b64 v[6:7], 15, v[4:5]
	s_mov_b64 s[24:25], 0x10000
	v_lshl_add_u64 v[10:11], v[6:7], 0, s[24:25]
	s_mov_b64 s[24:25], 0x18000
	v_readlane_b32 s0, v252, 20
	v_add_u32_e32 v22, 8, v4
	v_lshl_add_u64 v[12:13], v[6:7], 0, s[24:25]
	s_mov_b64 s[24:25], 0x20000
	v_readlane_b32 s1, v252, 21
	v_add_u32_e32 v75, 0x81, v3
	v_lshl_add_u64 v[14:15], v[6:7], 0, s[24:25]
	s_mov_b64 s[24:25], 0x28000
	v_ashrrev_i32_e32 v23, 31, v22
	v_lshlrev_b32_e32 v2, 2, v0
	s_lshl_b64 s[12:13], s[0:1], 12
	v_cmp_le_i32_e64 s[4:5], v22, v75
	v_lshl_add_u64 v[16:17], v[6:7], 0, s[24:25]
	s_mov_b64 s[24:25], 0x30000
	v_lshlrev_b64 v[22:23], 15, v[22:23]
	v_add_u32_e32 v27, 0, v2
	v_add_u32_e32 v76, 0x71, v3
	v_lshlrev_b32_e32 v30, 9, v1
	v_lshl_add_u64 v[18:19], v[6:7], 0, s[24:25]
	s_mov_b64 s[24:25], 0x38000
	v_or_b32_e32 v28, s12, v0
	v_mov_b32_e32 v29, s13
	v_mov_b32_e32 v3, v113
	v_or_b32_e32 v22, v22, v2
	v_mov_b32_e32 v100, 0
	v_cmp_lt_i32_e64 s[6:7], 0, v1
	v_cmp_eq_u32_e64 s[8:9], 7, v1
	s_lshl_b64 s[0:1], s[0:1], 7
	v_lshl_add_u64 v[8:9], v[6:7], 0, s[62:63]
	v_lshl_add_u64 v[20:21], v[6:7], 0, s[24:25]
	v_lshl_add_u64 v[22:23], s[66:67], 0, v[22:23]
	v_lshl_add_u64 v[24:25], s[66:67], 0, v[2:3]
	v_lshlrev_b32_e32 v26, 1, v0
	v_lshlrev_b64 v[28:29], 3, v[28:29]
	v_add_u32_e32 v3, v27, v30
	v_mov_b64_e32 v[38:39], 0
	v_mov_b32_e32 v108, 0
	v_mov_b64_e32 v[36:37], 0
	v_mov_b32_e32 v105, 0
	v_mov_b64_e32 v[32:33], 0
	v_mov_b32_e32 v103, 0
	v_mov_b64_e32 v[30:31], 0
	v_mov_b64_e32 v[118:119], 0
	v_mov_b32_e32 v117, 0
	v_mov_b32_e32 v115, 0
	v_mov_b64_e32 v[110:111], 0
	v_mov_b64_e32 v[124:125], 0
	v_mov_b64_e32 v[44:45], 0
	v_mov_b64_e32 v[122:123], 0
	v_mov_b64_e32 v[42:43], 0
	v_mov_b64_e32 v[120:121], 0
	v_mov_b64_e32 v[40:41], 0
	v_mov_b64_e32 v[34:35], 0
	s_branch .LBB0_350
